# FFN1 out-projection epilogue fused with the gated residual (X, xg, row sum-of-squares partials; f32 accumulators, nt streams); residual row pass removed
# speedup vs baseline: 1.0419x; 1.0095x over previous
.LBB0_328:
	s_lshr_b32 s32, s85, 4
	s_mul_i32 s32, s32, 0x9000
	s_add_u32 s48, s72, s32
	s_addc_u32 s49, s73, 0
	s_add_u32 s48, s48, 0x500000
	s_addc_u32 s49, s49, 0
	s_add_u32 s56, s72, 0x5000000
	s_addc_u32 s57, s73, 0
	s_add_u32 s58, s72, 0x1c000000
	s_addc_u32 s59, s73, 0
	v_lshl_or_b32 v241, s88, 8, v148
	v_lshlrev_b32_e32 v240, 2, v241
	s_add_u32 s68, s48, 0x2000
	s_addc_u32 s69, s49, 0
	global_load_dwordx4 v[160:163], v240, s[68:69]
	global_load_dwordx4 v[164:167], v240, s[68:69] offset:16
	global_load_dwordx4 v[168:171], v240, s[68:69] offset:512
	global_load_dwordx4 v[172:175], v240, s[68:69] offset:528
	s_add_u32 s68, s48, 0x4000
	s_addc_u32 s69, s49, 0
	global_load_dwordx4 v[190:193], v240, s[68:69]
	global_load_dwordx4 v[194:197], v240, s[68:69] offset:16
	global_load_dwordx4 v[198:201], v240, s[68:69] offset:512
	global_load_dwordx4 v[202:205], v240, s[68:69] offset:528
	global_load_dwordx4 v[208:211], v240, s[30:31]
	global_load_dwordx4 v[212:215], v240, s[30:31] offset:16
	global_load_dwordx4 v[216:219], v240, s[30:31] offset:512
	global_load_dwordx4 v[220:223], v240, s[30:31] offset:528
	v_lshl_add_u32 v241, s85, 8, v146
	v_lshl_add_u32 v152, v241, 12, v240
	v_add_u32_e32 v153, 0x10000, v152
	v_add_u32_e32 v154, 0x20000, v152
	v_add_u32_e32 v155, 0x30000, v152
	v_add_u32_e32 v156, 0x80000, v152
	v_add_u32_e32 v157, 0x90000, v152
	v_add_u32_e32 v158, 0xa0000, v152
	v_add_u32_e32 v159, 0xb0000, v152
	v_lshrrev_b32_e32 v184, 5, v148
	v_lshl_add_u32 v184, s88, 2, v184
	v_lshlrev_b32_e32 v184, 2, v184
	v_lshl_add_u32 v184, v241, 6, v184
	v_mov_b32_e32 v176, 0
	v_mov_b32_e32 v177, 0
	v_mov_b32_e32 v178, 0
	v_mov_b32_e32 v179, 0
	v_mov_b32_e32 v180, 0
	v_mov_b32_e32 v181, 0
	v_mov_b32_e32 v182, 0
	v_mov_b32_e32 v183, 0
	s_waitcnt vmcnt(0)
	v_pk_mul_f32 v[160:161], v[160:161], 0.5 op_sel_hi:[1,0]
	v_pk_mul_f32 v[162:163], v[162:163], 0.5 op_sel_hi:[1,0]
	v_pk_mul_f32 v[164:165], v[164:165], 0.5 op_sel_hi:[1,0]
	v_pk_mul_f32 v[166:167], v[166:167], 0.5 op_sel_hi:[1,0]
	v_pk_mul_f32 v[168:169], v[168:169], 0.5 op_sel_hi:[1,0]
	v_pk_mul_f32 v[170:171], v[170:171], 0.5 op_sel_hi:[1,0]
	v_pk_mul_f32 v[172:173], v[172:173], 0.5 op_sel_hi:[1,0]
	v_pk_mul_f32 v[174:175], v[174:175], 0.5 op_sel_hi:[1,0]
	v_pk_add_f32 v[190:191], v[190:191], 1.0 op_sel_hi:[1,0]
	v_pk_add_f32 v[192:193], v[192:193], 1.0 op_sel_hi:[1,0]
	v_pk_add_f32 v[194:195], v[194:195], 1.0 op_sel_hi:[1,0]
	v_pk_add_f32 v[196:197], v[196:197], 1.0 op_sel_hi:[1,0]
	v_pk_add_f32 v[198:199], v[198:199], 1.0 op_sel_hi:[1,0]
	v_pk_add_f32 v[200:201], v[200:201], 1.0 op_sel_hi:[1,0]
	v_pk_add_f32 v[202:203], v[202:203], 1.0 op_sel_hi:[1,0]
	v_pk_add_f32 v[204:205], v[204:205], 1.0 op_sel_hi:[1,0]
	v_pk_mul_f32 v[190:191], v[208:209], v[190:191]
	v_pk_mul_f32 v[192:193], v[210:211], v[192:193]
	v_pk_mul_f32 v[194:195], v[212:213], v[194:195]
	v_pk_mul_f32 v[196:197], v[214:215], v[196:197]
	v_pk_mul_f32 v[198:199], v[216:217], v[198:199]
	v_pk_mul_f32 v[200:201], v[218:219], v[200:201]
	v_pk_mul_f32 v[202:203], v[220:221], v[202:203]
	v_pk_mul_f32 v[204:205], v[222:223], v[204:205]
	global_load_dwordx4 v[208:211], v152, s[16:17] nt
	global_load_dwordx4 v[212:215], v152, s[16:17] offset:16 nt
	global_load_dwordx4 v[216:219], v153, s[16:17] nt
	global_load_dwordx4 v[220:223], v153, s[16:17] offset:16 nt
	global_load_dwordx4 v[224:227], v154, s[16:17] nt
	global_load_dwordx4 v[228:231], v154, s[16:17] offset:16 nt
	global_load_dwordx4 v[232:235], v155, s[16:17] nt
	global_load_dwordx4 v[236:239], v155, s[16:17] offset:16 nt
	s_waitcnt vmcnt(0)
	v_pk_fma_f32 v[208:209], v[160:161], v[124:125], v[208:209]
	v_pk_fma_f32 v[210:211], v[162:163], v[126:127], v[210:211]
	v_pk_fma_f32 v[212:213], v[164:165], v[120:121], v[212:213]
	v_pk_fma_f32 v[214:215], v[166:167], v[122:123], v[214:215]
	v_fmac_f32_e32 v176, v208, v208
	v_fmac_f32_e32 v176, v209, v209
	v_fmac_f32_e32 v176, v210, v210
	v_fmac_f32_e32 v176, v211, v211
	v_fmac_f32_e32 v176, v212, v212
	v_fmac_f32_e32 v176, v213, v213
	v_fmac_f32_e32 v176, v214, v214
	v_fmac_f32_e32 v176, v215, v215
	global_store_dwordx4 v152, v[208:211], s[70:71] nt
	global_store_dwordx4 v152, v[212:215], s[70:71] offset:16 nt
	v_pk_fma_f32 v[216:217], v[160:161], v[116:117], v[216:217]
	v_pk_fma_f32 v[218:219], v[162:163], v[118:119], v[218:219]
	v_pk_fma_f32 v[220:221], v[164:165], v[108:109], v[220:221]
	v_pk_fma_f32 v[222:223], v[166:167], v[110:111], v[222:223]
	v_fmac_f32_e32 v177, v216, v216
	v_fmac_f32_e32 v177, v217, v217
	v_fmac_f32_e32 v177, v218, v218
	v_fmac_f32_e32 v177, v219, v219
	v_fmac_f32_e32 v177, v220, v220
	v_fmac_f32_e32 v177, v221, v221
	v_fmac_f32_e32 v177, v222, v222
	v_fmac_f32_e32 v177, v223, v223
	global_store_dwordx4 v153, v[216:219], s[70:71] nt
	global_store_dwordx4 v153, v[220:223], s[70:71] offset:16 nt
	v_pk_mul_f32 v[208:209], v[208:209], v[190:191]
	v_pk_mul_f32 v[210:211], v[210:211], v[192:193]
	v_pk_mul_f32 v[212:213], v[212:213], v[194:195]
	v_pk_mul_f32 v[214:215], v[214:215], v[196:197]
	v_cvt_pk_bf16_f32 v208, v208, v209
	v_cvt_pk_bf16_f32 v209, v210, v211
	v_cvt_pk_bf16_f32 v210, v212, v213
	v_cvt_pk_bf16_f32 v211, v214, v215
	v_lshrrev_b32_e32 v144, 1, v152
	global_store_dwordx4 v144, v[208:211], s[56:57]
	v_pk_fma_f32 v[224:225], v[160:161], v[100:101], v[224:225]
	v_pk_fma_f32 v[226:227], v[162:163], v[102:103], v[226:227]
	v_pk_fma_f32 v[228:229], v[164:165], v[92:93], v[228:229]
	v_pk_fma_f32 v[230:231], v[166:167], v[94:95], v[230:231]
	v_fmac_f32_e32 v178, v224, v224
	v_fmac_f32_e32 v178, v225, v225
	v_fmac_f32_e32 v178, v226, v226
	v_fmac_f32_e32 v178, v227, v227
	v_fmac_f32_e32 v178, v228, v228
	v_fmac_f32_e32 v178, v229, v229
	v_fmac_f32_e32 v178, v230, v230
	v_fmac_f32_e32 v178, v231, v231
	global_store_dwordx4 v154, v[224:227], s[70:71] nt
	global_store_dwordx4 v154, v[228:231], s[70:71] offset:16 nt
	v_pk_mul_f32 v[216:217], v[216:217], v[190:191]
	v_pk_mul_f32 v[218:219], v[218:219], v[192:193]
	v_pk_mul_f32 v[220:221], v[220:221], v[194:195]
	v_pk_mul_f32 v[222:223], v[222:223], v[196:197]
	v_cvt_pk_bf16_f32 v216, v216, v217
	v_cvt_pk_bf16_f32 v217, v218, v219
	v_cvt_pk_bf16_f32 v218, v220, v221
	v_cvt_pk_bf16_f32 v219, v222, v223
	v_lshrrev_b32_e32 v144, 1, v153
	global_store_dwordx4 v144, v[216:219], s[56:57]
	v_pk_fma_f32 v[232:233], v[160:161], v[84:85], v[232:233]
	v_pk_fma_f32 v[234:235], v[162:163], v[86:87], v[234:235]
	v_pk_fma_f32 v[236:237], v[164:165], v[76:77], v[236:237]
	v_pk_fma_f32 v[238:239], v[166:167], v[78:79], v[238:239]
	v_fmac_f32_e32 v179, v232, v232
	v_fmac_f32_e32 v179, v233, v233
	v_fmac_f32_e32 v179, v234, v234
	v_fmac_f32_e32 v179, v235, v235
	v_fmac_f32_e32 v179, v236, v236
	v_fmac_f32_e32 v179, v237, v237
	v_fmac_f32_e32 v179, v238, v238
	v_fmac_f32_e32 v179, v239, v239
	global_store_dwordx4 v155, v[232:235], s[70:71] nt
	global_store_dwordx4 v155, v[236:239], s[70:71] offset:16 nt
	v_pk_mul_f32 v[224:225], v[224:225], v[190:191]
	v_pk_mul_f32 v[226:227], v[226:227], v[192:193]
	v_pk_mul_f32 v[228:229], v[228:229], v[194:195]
	v_pk_mul_f32 v[230:231], v[230:231], v[196:197]
	v_cvt_pk_bf16_f32 v224, v224, v225
	v_cvt_pk_bf16_f32 v225, v226, v227
	v_cvt_pk_bf16_f32 v226, v228, v229
	v_cvt_pk_bf16_f32 v227, v230, v231
	v_lshrrev_b32_e32 v144, 1, v154
	global_store_dwordx4 v144, v[224:227], s[56:57]
	s_nop 1
	v_pk_mul_f32 v[232:233], v[232:233], v[190:191]
	v_pk_mul_f32 v[234:235], v[234:235], v[192:193]
	v_pk_mul_f32 v[236:237], v[236:237], v[194:195]
	v_pk_mul_f32 v[238:239], v[238:239], v[196:197]
	v_cvt_pk_bf16_f32 v232, v232, v233
	v_cvt_pk_bf16_f32 v233, v234, v235
	v_cvt_pk_bf16_f32 v234, v236, v237
	v_cvt_pk_bf16_f32 v235, v238, v239
	v_lshrrev_b32_e32 v144, 1, v155
	global_store_dwordx4 v144, v[232:235], s[56:57]
	global_load_dwordx4 v[208:211], v156, s[16:17] nt
	global_load_dwordx4 v[212:215], v156, s[16:17] offset:16 nt
	global_load_dwordx4 v[216:219], v157, s[16:17] nt
	global_load_dwordx4 v[220:223], v157, s[16:17] offset:16 nt
	global_load_dwordx4 v[224:227], v158, s[16:17] nt
	global_load_dwordx4 v[228:231], v158, s[16:17] offset:16 nt
	global_load_dwordx4 v[232:235], v159, s[16:17] nt
	global_load_dwordx4 v[236:239], v159, s[16:17] offset:16 nt
	s_waitcnt vmcnt(0)
	v_pk_fma_f32 v[208:209], v[160:161], v[60:61], v[208:209]
	v_pk_fma_f32 v[210:211], v[162:163], v[62:63], v[210:211]
	v_pk_fma_f32 v[212:213], v[164:165], v[56:57], v[212:213]
	v_pk_fma_f32 v[214:215], v[166:167], v[58:59], v[214:215]
	v_fmac_f32_e32 v180, v208, v208
	v_fmac_f32_e32 v180, v209, v209
	v_fmac_f32_e32 v180, v210, v210
	v_fmac_f32_e32 v180, v211, v211
	v_fmac_f32_e32 v180, v212, v212
	v_fmac_f32_e32 v180, v213, v213
	v_fmac_f32_e32 v180, v214, v214
	v_fmac_f32_e32 v180, v215, v215
	global_store_dwordx4 v156, v[208:211], s[70:71] nt
	global_store_dwordx4 v156, v[212:215], s[70:71] offset:16 nt
	v_pk_fma_f32 v[216:217], v[160:161], v[52:53], v[216:217]
	v_pk_fma_f32 v[218:219], v[162:163], v[54:55], v[218:219]
	v_pk_fma_f32 v[220:221], v[164:165], v[44:45], v[220:221]
	v_pk_fma_f32 v[222:223], v[166:167], v[46:47], v[222:223]
	v_fmac_f32_e32 v181, v216, v216
	v_fmac_f32_e32 v181, v217, v217
	v_fmac_f32_e32 v181, v218, v218
	v_fmac_f32_e32 v181, v219, v219
	v_fmac_f32_e32 v181, v220, v220
	v_fmac_f32_e32 v181, v221, v221
	v_fmac_f32_e32 v181, v222, v222
	v_fmac_f32_e32 v181, v223, v223
	global_store_dwordx4 v157, v[216:219], s[70:71] nt
	global_store_dwordx4 v157, v[220:223], s[70:71] offset:16 nt
	v_pk_mul_f32 v[208:209], v[208:209], v[190:191]
	v_pk_mul_f32 v[210:211], v[210:211], v[192:193]
	v_pk_mul_f32 v[212:213], v[212:213], v[194:195]
	v_pk_mul_f32 v[214:215], v[214:215], v[196:197]
	v_cvt_pk_bf16_f32 v208, v208, v209
	v_cvt_pk_bf16_f32 v209, v210, v211
	v_cvt_pk_bf16_f32 v210, v212, v213
	v_cvt_pk_bf16_f32 v211, v214, v215
	v_lshrrev_b32_e32 v144, 1, v156
	global_store_dwordx4 v144, v[208:211], s[56:57]
	v_pk_fma_f32 v[224:225], v[160:161], v[36:37], v[224:225]
	v_pk_fma_f32 v[226:227], v[162:163], v[38:39], v[226:227]
	v_pk_fma_f32 v[228:229], v[164:165], v[28:29], v[228:229]
	v_pk_fma_f32 v[230:231], v[166:167], v[30:31], v[230:231]
	v_fmac_f32_e32 v182, v224, v224
	v_fmac_f32_e32 v182, v225, v225
	v_fmac_f32_e32 v182, v226, v226
	v_fmac_f32_e32 v182, v227, v227
	v_fmac_f32_e32 v182, v228, v228
	v_fmac_f32_e32 v182, v229, v229
	v_fmac_f32_e32 v182, v230, v230
	v_fmac_f32_e32 v182, v231, v231
	global_store_dwordx4 v158, v[224:227], s[70:71] nt
	global_store_dwordx4 v158, v[228:231], s[70:71] offset:16 nt
	v_pk_mul_f32 v[216:217], v[216:217], v[190:191]
	v_pk_mul_f32 v[218:219], v[218:219], v[192:193]
	v_pk_mul_f32 v[220:221], v[220:221], v[194:195]
	v_pk_mul_f32 v[222:223], v[222:223], v[196:197]
	v_cvt_pk_bf16_f32 v216, v216, v217
	v_cvt_pk_bf16_f32 v217, v218, v219
	v_cvt_pk_bf16_f32 v218, v220, v221
	v_cvt_pk_bf16_f32 v219, v222, v223
	v_lshrrev_b32_e32 v144, 1, v157
	global_store_dwordx4 v144, v[216:219], s[56:57]
	v_pk_fma_f32 v[232:233], v[160:161], v[20:21], v[232:233]
	v_pk_fma_f32 v[234:235], v[162:163], v[22:23], v[234:235]
	v_pk_fma_f32 v[236:237], v[164:165], v[12:13], v[236:237]
	v_pk_fma_f32 v[238:239], v[166:167], v[14:15], v[238:239]
	v_fmac_f32_e32 v183, v232, v232
	v_fmac_f32_e32 v183, v233, v233
	v_fmac_f32_e32 v183, v234, v234
	v_fmac_f32_e32 v183, v235, v235
	v_fmac_f32_e32 v183, v236, v236
	v_fmac_f32_e32 v183, v237, v237
	v_fmac_f32_e32 v183, v238, v238
	v_fmac_f32_e32 v183, v239, v239
	global_store_dwordx4 v159, v[232:235], s[70:71] nt
	global_store_dwordx4 v159, v[236:239], s[70:71] offset:16 nt
	v_pk_mul_f32 v[224:225], v[224:225], v[190:191]
	v_pk_mul_f32 v[226:227], v[226:227], v[192:193]
	v_pk_mul_f32 v[228:229], v[228:229], v[194:195]
	v_pk_mul_f32 v[230:231], v[230:231], v[196:197]
	v_cvt_pk_bf16_f32 v224, v224, v225
	v_cvt_pk_bf16_f32 v225, v226, v227
	v_cvt_pk_bf16_f32 v226, v228, v229
	v_cvt_pk_bf16_f32 v227, v230, v231
	v_lshrrev_b32_e32 v144, 1, v158
	global_store_dwordx4 v144, v[224:227], s[56:57]
	s_nop 1
	v_pk_mul_f32 v[232:233], v[232:233], v[190:191]
	v_pk_mul_f32 v[234:235], v[234:235], v[192:193]
	v_pk_mul_f32 v[236:237], v[236:237], v[194:195]
	v_pk_mul_f32 v[238:239], v[238:239], v[196:197]
	v_cvt_pk_bf16_f32 v232, v232, v233
	v_cvt_pk_bf16_f32 v233, v234, v235
	v_cvt_pk_bf16_f32 v234, v236, v237
	v_cvt_pk_bf16_f32 v235, v238, v239
	v_lshrrev_b32_e32 v144, 1, v159
	global_store_dwordx4 v144, v[232:235], s[56:57]
	global_load_dwordx4 v[208:211], v152, s[16:17] offset:512 nt
	global_load_dwordx4 v[212:215], v152, s[16:17] offset:528 nt
	global_load_dwordx4 v[216:219], v153, s[16:17] offset:512 nt
	global_load_dwordx4 v[220:223], v153, s[16:17] offset:528 nt
	global_load_dwordx4 v[224:227], v154, s[16:17] offset:512 nt
	global_load_dwordx4 v[228:231], v154, s[16:17] offset:528 nt
	global_load_dwordx4 v[232:235], v155, s[16:17] offset:512 nt
	global_load_dwordx4 v[236:239], v155, s[16:17] offset:528 nt
	s_waitcnt vmcnt(0)
	v_pk_fma_f32 v[208:209], v[168:169], v[112:113], v[208:209]
	v_pk_fma_f32 v[210:211], v[170:171], v[114:115], v[210:211]
	v_pk_fma_f32 v[212:213], v[172:173], v[104:105], v[212:213]
	v_pk_fma_f32 v[214:215], v[174:175], v[106:107], v[214:215]
	v_fmac_f32_e32 v176, v208, v208
	v_fmac_f32_e32 v176, v209, v209
	v_fmac_f32_e32 v176, v210, v210
	v_fmac_f32_e32 v176, v211, v211
	v_fmac_f32_e32 v176, v212, v212
	v_fmac_f32_e32 v176, v213, v213
	v_fmac_f32_e32 v176, v214, v214
	v_fmac_f32_e32 v176, v215, v215
	global_store_dwordx4 v152, v[208:211], s[70:71] offset:512 nt
	global_store_dwordx4 v152, v[212:215], s[70:71] offset:528 nt
	v_pk_fma_f32 v[216:217], v[168:169], v[96:97], v[216:217]
	v_pk_fma_f32 v[218:219], v[170:171], v[98:99], v[218:219]
	v_pk_fma_f32 v[220:221], v[172:173], v[88:89], v[220:221]
	v_pk_fma_f32 v[222:223], v[174:175], v[90:91], v[222:223]
	v_fmac_f32_e32 v177, v216, v216
	v_fmac_f32_e32 v177, v217, v217
	v_fmac_f32_e32 v177, v218, v218
	v_fmac_f32_e32 v177, v219, v219
	v_fmac_f32_e32 v177, v220, v220
	v_fmac_f32_e32 v177, v221, v221
	v_fmac_f32_e32 v177, v222, v222
	v_fmac_f32_e32 v177, v223, v223
	global_store_dwordx4 v153, v[216:219], s[70:71] offset:512 nt
	global_store_dwordx4 v153, v[220:223], s[70:71] offset:528 nt
	v_pk_mul_f32 v[208:209], v[208:209], v[198:199]
	v_pk_mul_f32 v[210:211], v[210:211], v[200:201]
	v_pk_mul_f32 v[212:213], v[212:213], v[202:203]
	v_pk_mul_f32 v[214:215], v[214:215], v[204:205]
	v_cvt_pk_bf16_f32 v208, v208, v209
	v_cvt_pk_bf16_f32 v209, v210, v211
	v_cvt_pk_bf16_f32 v210, v212, v213
	v_cvt_pk_bf16_f32 v211, v214, v215
	v_lshrrev_b32_e32 v144, 1, v152
	global_store_dwordx4 v144, v[208:211], s[56:57] offset:256
	v_pk_fma_f32 v[224:225], v[168:169], v[80:81], v[224:225]
	v_pk_fma_f32 v[226:227], v[170:171], v[82:83], v[226:227]
	v_pk_fma_f32 v[228:229], v[172:173], v[72:73], v[228:229]
	v_pk_fma_f32 v[230:231], v[174:175], v[74:75], v[230:231]
	v_fmac_f32_e32 v178, v224, v224
	v_fmac_f32_e32 v178, v225, v225
	v_fmac_f32_e32 v178, v226, v226
	v_fmac_f32_e32 v178, v227, v227
	v_fmac_f32_e32 v178, v228, v228
	v_fmac_f32_e32 v178, v229, v229
	v_fmac_f32_e32 v178, v230, v230
	v_fmac_f32_e32 v178, v231, v231
	global_store_dwordx4 v154, v[224:227], s[70:71] offset:512 nt
	global_store_dwordx4 v154, v[228:231], s[70:71] offset:528 nt
	v_pk_mul_f32 v[216:217], v[216:217], v[198:199]
	v_pk_mul_f32 v[218:219], v[218:219], v[200:201]
	v_pk_mul_f32 v[220:221], v[220:221], v[202:203]
	v_pk_mul_f32 v[222:223], v[222:223], v[204:205]
	v_cvt_pk_bf16_f32 v216, v216, v217
	v_cvt_pk_bf16_f32 v217, v218, v219
	v_cvt_pk_bf16_f32 v218, v220, v221
	v_cvt_pk_bf16_f32 v219, v222, v223
	v_lshrrev_b32_e32 v144, 1, v153
	global_store_dwordx4 v144, v[216:219], s[56:57] offset:256
	v_pk_fma_f32 v[232:233], v[168:169], v[68:69], v[232:233]
	v_pk_fma_f32 v[234:235], v[170:171], v[70:71], v[234:235]
	v_pk_fma_f32 v[236:237], v[172:173], v[64:65], v[236:237]
	v_pk_fma_f32 v[238:239], v[174:175], v[66:67], v[238:239]
	v_fmac_f32_e32 v179, v232, v232
	v_fmac_f32_e32 v179, v233, v233
	v_fmac_f32_e32 v179, v234, v234
	v_fmac_f32_e32 v179, v235, v235
	v_fmac_f32_e32 v179, v236, v236
	v_fmac_f32_e32 v179, v237, v237
	v_fmac_f32_e32 v179, v238, v238
	v_fmac_f32_e32 v179, v239, v239
	global_store_dwordx4 v155, v[232:235], s[70:71] offset:512 nt
	global_store_dwordx4 v155, v[236:239], s[70:71] offset:528 nt
	v_pk_mul_f32 v[224:225], v[224:225], v[198:199]
	v_pk_mul_f32 v[226:227], v[226:227], v[200:201]
	v_pk_mul_f32 v[228:229], v[228:229], v[202:203]
	v_pk_mul_f32 v[230:231], v[230:231], v[204:205]
	v_cvt_pk_bf16_f32 v224, v224, v225
	v_cvt_pk_bf16_f32 v225, v226, v227
	v_cvt_pk_bf16_f32 v226, v228, v229
	v_cvt_pk_bf16_f32 v227, v230, v231
	v_lshrrev_b32_e32 v144, 1, v154
	global_store_dwordx4 v144, v[224:227], s[56:57] offset:256
	s_nop 1
	v_pk_mul_f32 v[232:233], v[232:233], v[198:199]
	v_pk_mul_f32 v[234:235], v[234:235], v[200:201]
	v_pk_mul_f32 v[236:237], v[236:237], v[202:203]
	v_pk_mul_f32 v[238:239], v[238:239], v[204:205]
	v_cvt_pk_bf16_f32 v232, v232, v233
	v_cvt_pk_bf16_f32 v233, v234, v235
	v_cvt_pk_bf16_f32 v234, v236, v237
	v_cvt_pk_bf16_f32 v235, v238, v239
	v_lshrrev_b32_e32 v144, 1, v155
	global_store_dwordx4 v144, v[232:235], s[56:57] offset:256
	global_load_dwordx4 v[208:211], v156, s[16:17] offset:512 nt
	global_load_dwordx4 v[212:215], v156, s[16:17] offset:528 nt
	global_load_dwordx4 v[216:219], v157, s[16:17] offset:512 nt
	global_load_dwordx4 v[220:223], v157, s[16:17] offset:528 nt
	global_load_dwordx4 v[224:227], v158, s[16:17] offset:512 nt
	global_load_dwordx4 v[228:231], v158, s[16:17] offset:528 nt
	global_load_dwordx4 v[232:235], v159, s[16:17] offset:512 nt
	global_load_dwordx4 v[236:239], v159, s[16:17] offset:528 nt
	s_waitcnt vmcnt(0)
	v_pk_fma_f32 v[208:209], v[168:169], v[48:49], v[208:209]
	v_pk_fma_f32 v[210:211], v[170:171], v[50:51], v[210:211]
	v_pk_fma_f32 v[212:213], v[172:173], v[40:41], v[212:213]
	v_pk_fma_f32 v[214:215], v[174:175], v[42:43], v[214:215]
	v_fmac_f32_e32 v180, v208, v208
	v_fmac_f32_e32 v180, v209, v209
	v_fmac_f32_e32 v180, v210, v210
	v_fmac_f32_e32 v180, v211, v211
	v_fmac_f32_e32 v180, v212, v212
	v_fmac_f32_e32 v180, v213, v213
	v_fmac_f32_e32 v180, v214, v214
	v_fmac_f32_e32 v180, v215, v215
	global_store_dwordx4 v156, v[208:211], s[70:71] offset:512 nt
	global_store_dwordx4 v156, v[212:215], s[70:71] offset:528 nt
	v_pk_fma_f32 v[216:217], v[168:169], v[32:33], v[216:217]
	v_pk_fma_f32 v[218:219], v[170:171], v[34:35], v[218:219]
	v_pk_fma_f32 v[220:221], v[172:173], v[24:25], v[220:221]
	v_pk_fma_f32 v[222:223], v[174:175], v[26:27], v[222:223]
	v_fmac_f32_e32 v181, v216, v216
	v_fmac_f32_e32 v181, v217, v217
	v_fmac_f32_e32 v181, v218, v218
	v_fmac_f32_e32 v181, v219, v219
	v_fmac_f32_e32 v181, v220, v220
	v_fmac_f32_e32 v181, v221, v221
	v_fmac_f32_e32 v181, v222, v222
	v_fmac_f32_e32 v181, v223, v223
	global_store_dwordx4 v157, v[216:219], s[70:71] offset:512 nt
	global_store_dwordx4 v157, v[220:223], s[70:71] offset:528 nt
	v_pk_mul_f32 v[208:209], v[208:209], v[198:199]
	v_pk_mul_f32 v[210:211], v[210:211], v[200:201]
	v_pk_mul_f32 v[212:213], v[212:213], v[202:203]
	v_pk_mul_f32 v[214:215], v[214:215], v[204:205]
	v_cvt_pk_bf16_f32 v208, v208, v209
	v_cvt_pk_bf16_f32 v209, v210, v211
	v_cvt_pk_bf16_f32 v210, v212, v213
	v_cvt_pk_bf16_f32 v211, v214, v215
	v_lshrrev_b32_e32 v144, 1, v156
	global_store_dwordx4 v144, v[208:211], s[56:57] offset:256
	v_pk_fma_f32 v[224:225], v[168:169], v[16:17], v[224:225]
	v_pk_fma_f32 v[226:227], v[170:171], v[18:19], v[226:227]
	v_pk_fma_f32 v[228:229], v[172:173], v[8:9], v[228:229]
	v_pk_fma_f32 v[230:231], v[174:175], v[10:11], v[230:231]
	v_fmac_f32_e32 v182, v224, v224
	v_fmac_f32_e32 v182, v225, v225
	v_fmac_f32_e32 v182, v226, v226
	v_fmac_f32_e32 v182, v227, v227
	v_fmac_f32_e32 v182, v228, v228
	v_fmac_f32_e32 v182, v229, v229
	v_fmac_f32_e32 v182, v230, v230
	v_fmac_f32_e32 v182, v231, v231
	global_store_dwordx4 v158, v[224:227], s[70:71] offset:512 nt
	global_store_dwordx4 v158, v[228:231], s[70:71] offset:528 nt
	v_pk_mul_f32 v[216:217], v[216:217], v[198:199]
	v_pk_mul_f32 v[218:219], v[218:219], v[200:201]
	v_pk_mul_f32 v[220:221], v[220:221], v[202:203]
	v_pk_mul_f32 v[222:223], v[222:223], v[204:205]
	v_cvt_pk_bf16_f32 v216, v216, v217
	v_cvt_pk_bf16_f32 v217, v218, v219
	v_cvt_pk_bf16_f32 v218, v220, v221
	v_cvt_pk_bf16_f32 v219, v222, v223
	v_lshrrev_b32_e32 v144, 1, v157
	global_store_dwordx4 v144, v[216:219], s[56:57] offset:256
	v_pk_fma_f32 v[232:233], v[168:169], v[4:5], v[232:233]
	v_pk_fma_f32 v[234:235], v[170:171], v[6:7], v[234:235]
	v_pk_fma_f32 v[236:237], v[172:173], v[0:1], v[236:237]
	v_pk_fma_f32 v[238:239], v[174:175], v[2:3], v[238:239]
	v_fmac_f32_e32 v183, v232, v232
	v_fmac_f32_e32 v183, v233, v233
	v_fmac_f32_e32 v183, v234, v234
	v_fmac_f32_e32 v183, v235, v235
	v_fmac_f32_e32 v183, v236, v236
	v_fmac_f32_e32 v183, v237, v237
	v_fmac_f32_e32 v183, v238, v238
	v_fmac_f32_e32 v183, v239, v239
	global_store_dwordx4 v159, v[232:235], s[70:71] offset:512 nt
	global_store_dwordx4 v159, v[236:239], s[70:71] offset:528 nt
	v_pk_mul_f32 v[224:225], v[224:225], v[198:199]
	v_pk_mul_f32 v[226:227], v[226:227], v[200:201]
	v_pk_mul_f32 v[228:229], v[228:229], v[202:203]
	v_pk_mul_f32 v[230:231], v[230:231], v[204:205]
	v_cvt_pk_bf16_f32 v224, v224, v225
	v_cvt_pk_bf16_f32 v225, v226, v227
	v_cvt_pk_bf16_f32 v226, v228, v229
	v_cvt_pk_bf16_f32 v227, v230, v231
	v_lshrrev_b32_e32 v144, 1, v158
	global_store_dwordx4 v144, v[224:227], s[56:57] offset:256
	s_nop 1
	v_pk_mul_f32 v[232:233], v[232:233], v[198:199]
	v_pk_mul_f32 v[234:235], v[234:235], v[200:201]
	v_pk_mul_f32 v[236:237], v[236:237], v[202:203]
	v_pk_mul_f32 v[238:239], v[238:239], v[204:205]
	v_cvt_pk_bf16_f32 v232, v232, v233
	v_cvt_pk_bf16_f32 v233, v234, v235
	v_cvt_pk_bf16_f32 v234, v236, v237
	v_cvt_pk_bf16_f32 v235, v238, v239
	v_lshrrev_b32_e32 v144, 1, v159
	global_store_dwordx4 v144, v[232:235], s[56:57] offset:256
	v_and_b32_e32 v185, 63, v188
	v_xor_b32_e32 v186, 16, v185
	v_lshlrev_b32_e32 v186, 2, v186
	v_xor_b32_e32 v187, 32, v185
	v_lshlrev_b32_e32 v187, 2, v187
	s_waitcnt lgkmcnt(0)
	ds_bpermute_b32 v160, v186, v176
	ds_bpermute_b32 v161, v186, v177
	ds_bpermute_b32 v162, v186, v178
	ds_bpermute_b32 v163, v186, v179
	ds_bpermute_b32 v164, v186, v180
	ds_bpermute_b32 v165, v186, v181
	ds_bpermute_b32 v166, v186, v182
	ds_bpermute_b32 v167, v186, v183
	s_waitcnt lgkmcnt(0)
	v_add_f32_e32 v176, v176, v160
	v_add_f32_e32 v177, v177, v161
	v_add_f32_e32 v178, v178, v162
	v_add_f32_e32 v179, v179, v163
	v_add_f32_e32 v180, v180, v164
	v_add_f32_e32 v181, v181, v165
	v_add_f32_e32 v182, v182, v166
	v_add_f32_e32 v183, v183, v167
	ds_bpermute_b32 v160, v187, v176
	ds_bpermute_b32 v161, v187, v177
	ds_bpermute_b32 v162, v187, v178
	ds_bpermute_b32 v163, v187, v179
	ds_bpermute_b32 v164, v187, v180
	ds_bpermute_b32 v165, v187, v181
	ds_bpermute_b32 v166, v187, v182
	ds_bpermute_b32 v167, v187, v183
	s_waitcnt lgkmcnt(0)
	v_add_f32_e32 v176, v176, v160
	v_add_f32_e32 v177, v177, v161
	v_add_f32_e32 v178, v178, v162
	v_add_f32_e32 v179, v179, v163
	v_add_f32_e32 v180, v180, v164
	v_add_f32_e32 v181, v181, v165
	v_add_f32_e32 v182, v182, v166
	v_add_f32_e32 v183, v183, v167
	v_cmp_gt_u32_e32 vcc, 16, v185
	s_and_saveexec_b64 s[68:69], vcc
	global_store_dword v184, v176, s[58:59]
	v_add_u32_e32 v144, 0x400, v184
	global_store_dword v144, v177, s[58:59]
	v_add_u32_e32 v144, 0x800, v184
	global_store_dword v144, v178, s[58:59]
	v_add_u32_e32 v144, 0xc00, v184
	global_store_dword v144, v179, s[58:59]
	v_add_u32_e32 v144, 0x2000, v184
	global_store_dword v144, v180, s[58:59]
	v_add_u32_e32 v144, 0x2400, v184
	global_store_dword v144, v181, s[58:59]
	v_add_u32_e32 v144, 0x2800, v184
	global_store_dword v144, v182, s[58:59]
	v_add_u32_e32 v144, 0x2c00, v184
	global_store_dword v144, v183, s[58:59]
	s_or_b64 exec, exec, s[68:69]
	s_and_b64 vcc, exec, s[0:1]
	s_mov_b64 s[0:1], -1
	s_cbranch_vccnz .LBB0_313
	s_andn2_b64 vcc, exec, s[6:7]
	s_cbranch_vccnz .LBB0_312
	s_barrier
	s_branch .LBB0_312

.LBB0_403:
	s_and_b32 s27, s2, 7
	s_lshl_b32 s88, s27, 8
	s_and_b32 s85, s2, -8
	s_add_i32 s88, s88, s85
	s_add_i32 s3, s3, s88
	s_cmpk_gt_i32 s3, 0x7ff
	s_branch .LBB0_412
	s_waitcnt lgkmcnt(0)
	v_mbcnt_hi_u32_b32 v1, -1, v189
	v_and_b32_e32 v4, 64, v1
	v_add_u32_e32 v4, 64, v4
	v_xor_b32_e32 v5, 1, v1
	v_mov_b32_e32 v3, 0
	v_cmp_lt_i32_e32 vcc, v5, v4
	v_lshlrev_b32_e32 v50, 3, v162
	v_mov_b32_e32 v51, v3
	v_cndmask_b32_e32 v5, v1, v5, vcc
	v_lshl_add_u64 v[52:53], s[22:23], 0, v[50:51]
	v_lshlrev_b32_e32 v51, 2, v5
	v_xor_b32_e32 v5, 2, v1
	v_cmp_lt_i32_e32 vcc, v5, v4
	v_lshlrev_b32_e32 v0, 2, v162
	v_lshlrev_b32_e32 v2, 4, v162
	v_cndmask_b32_e32 v5, v1, v5, vcc
	v_lshlrev_b32_e32 v124, 2, v5
	v_xor_b32_e32 v5, 4, v1
	v_cmp_lt_i32_e32 vcc, v5, v4
	v_or_b32_e32 v6, 0x200, v0
	v_or_b32_e32 v8, 0x300, v0
	v_cndmask_b32_e32 v5, v1, v5, vcc
	v_lshlrev_b32_e32 v125, 2, v5
	v_xor_b32_e32 v5, 8, v1
	v_cmp_lt_i32_e32 vcc, v5, v4
	v_lshl_add_u64 v[10:11], s[72:73], 0, v[2:3]
	s_mov_b64 s[4:5], 0x502000
	v_cndmask_b32_e32 v5, v1, v5, vcc
	v_lshlrev_b32_e32 v126, 2, v5
	v_xor_b32_e32 v5, 16, v1
	v_cmp_lt_i32_e32 vcc, v5, v4
	v_lshl_add_u64 v[48:49], s[16:17], 0, v[2:3]
	v_cmp_eq_u32_e64 s[0:1], 0, v162
	v_cndmask_b32_e32 v5, v1, v5, vcc
	v_lshlrev_b32_e32 v127, 2, v5
	v_xor_b32_e32 v5, 32, v1
	v_cmp_lt_i32_e32 vcc, v5, v4
	v_or_b32_e32 v4, 0x100, v0
	v_lshl_add_u64 v[54:55], s[30:31], 0, v[2:3]
	v_cndmask_b32_e32 v1, v1, v5, vcc
	v_lshlrev_b32_e32 v128, 2, v1
	v_cmp_gt_u32_e32 vcc, 16, v162
	v_lshl_add_u64 v[56:57], v[10:11], 0, s[4:5]
	v_or_b32_e32 v58, 0x1c000000, v0
	v_mov_b32_e32 v59, v3
	s_lshl_b32 s6, s3, 4
	s_lshl_b32 s12, s74, 7
	v_lshl_add_u64 v[60:61], s[70:71], 0, v[2:3]
	v_lshlrev_b32_e32 v129, 2, v0
	v_mov_b32_e32 v130, 0x9000
	v_lshlrev_b32_e32 v131, 2, v4
	v_lshlrev_b32_e32 v132, 2, v6
	v_lshlrev_b32_e32 v133, 2, v8
	s_movk_i32 s13, 0x1000
	s_mov_b32 s34, 0x5000000
	s_mov_b64 s[8:9], 0x1000
	s_mov_b64 s[10:11], 0x800
